# GLA recurrence: shared gv/q LDS-DMA ring deepened from 4 to 5 slots (prefetch 4 chunks ahead)
# baseline (speedup 1.0000x reference)
; __device__ __forceinline__ void gla_item(LAS unsigned char* lds, int item, const bf16_t* KDT, const float* DEC, const bf16_t* GVT, const bf16_t* GQF, bf16_t* OG) {
;     ...
;     const bf16_t* kdt = KDT + (size_t)((b * 4 + h) * 32) * 8192 + (size_t)(wid * 2 * 64 + lane) * 8;
;     const float* dec = DEC + (size_t)((b * 4 + h) * 32) * 128 + 16 * wid + 4 * fq;
;     const bf16_t* gvt = GVT + (size_t)item * (32 * 4 * 512) + (size_t)lane * 8;
;     const int f0 = 16 * (wid & 3), v0 = 16 * (wid >> 2);
;     const bf16_t* gq = GQF + ((size_t)((b * 4 + h) * 32) * 16 + (size_t)(wid & 3) * 4) * 512 + (size_t)lane * 8;
;     bf16_t* outp = OG + (size_t)item * (SEQ * 32) + (size_t)(f0 + fr) * 32 + v0 + 4 * fq;
;     f32x4 S[2]; S[0] = (f32x4){0.f, 0.f, 0.f, 0.f}; S[1] = S[0];
;     ...
;     GlaSet s0, s1, s2;
;     GLA_LOAD(s0, 0); GLA_LOAD(s1, 1);
; #pragma unroll 1
;     for (int c = 0; c < 30; c += 3) {
;         GLA_LOAD(s2, c + 2); GLA_STEP(s0, c);
;         GLA_LOAD(s0, c + 3); GLA_STEP(s1, c + 1);
;         GLA_LOAD(s1, c + 4); GLA_STEP(s2, c + 2);
;     }
;     GLA_STEP(s0, 30); GLA_STEP(s1, 31);
.LBB0_982:
	v_readfirstlane_b32 s53, v185
	v_lshlrev_b32_e32 v0, 4, v184
	v_lshrrev_b32_e32 v6, 4, v184
	v_and_b32_e32 v7, 15, v184
	s_lshr_b32 s53, s53, 6
	v_lshlrev_b32_e32 v1, 4, v6
	s_and_b32 s0, s52, 7
	s_lshl_b32 s0, s0, 2
	s_lshr_b32 s55, s52, 6
	s_add_i32 s0, s0, s55
	s_bfe_u32 s55, s52, 0x30003
	s_lshl_b32 s69, s0, 3
	s_add_i32 s69, s69, s55
	s_lshl_b32 s36, s0, 19
	s_lshl_b32 s37, s53, 11
	s_add_i32 s36, s36, s37
	s_add_u32 s58, s86, 0x14000000
	s_addc_u32 s59, s87, 0
	s_add_u32 s58, s58, s36
	s_addc_u32 s59, s59, 0
	s_lshl_b32 s36, s0, 14
	s_lshl_b32 s37, s53, 6
	s_add_i32 s36, s36, s37
	s_add_u32 s60, s86, 0x15000000
	s_addc_u32 s61, s87, 0
	s_add_u32 s60, s60, s36
	s_addc_u32 s61, s61, 0
	s_lshl_b32 s36, s69, 17
	s_add_u32 s62, s86, 0x10800000
	s_addc_u32 s63, s87, 0
	s_add_u32 s62, s62, s36
	s_addc_u32 s63, s63, 0
	s_add_u32 s66, s86, 0x1e000000
	s_addc_u32 s67, s87, 0
	s_add_u32 s66, s66, s36
	s_addc_u32 s67, s67, 0
	s_and_b32 s36, s53, 3
	s_lshl_b32 s36, s36, 12
	s_lshr_b32 s37, s53, 2
	s_lshl_b32 s37, s37, 11
	s_add_i32 s55, s36, s37
	s_lshl_b32 s37, s0, 19
	s_add_u32 s64, s86, 0x6800000
	s_addc_u32 s65, s87, 0
	s_add_u32 s64, s64, s37
	s_addc_u32 s65, s65, 0
	s_add_u32 s64, s64, s55
	s_addc_u32 s65, s65, 0
	s_add_i32 s36, s36, 0x1000
	v_add_u32_e32 v108, s36, v0
	s_and_b32 s36, s53, 3
	s_lshl_b32 s36, s36, 4
	v_add_u32_e32 v2, s36, v7
	v_lshlrev_b32_e32 v2, 5, v2
	s_lshr_b32 s37, s53, 2
	s_lshl_b32 s37, s37, 4
	v_lshl_add_u32 v2, v6, 2, v2
	v_add_u32_e32 v2, s37, v2
	v_lshlrev_b32_e32 v2, 1, v2
	v_mul_u32_u24_e32 v3, 0x110, v7
	s_lshl_b32 s36, s53, 5
	v_lshl_add_u32 v3, v6, 3, v3
	v_add_u32_e32 v3, s36, v3
	v_add_u32_e32 v4, s37, v7
	v_mul_u32_u24_e32 v4, 0x110, v4
	v_lshl_add_u32 v4, v6, 4, v4
	s_lshr_b32 s36, s53, 1
	s_lshl_b32 s36, s36, 10
	v_add_u32_e32 v109, s36, v0
	s_and_b32 s37, s53, 1
	s_add_i32 s53, s55, 0x1000
	s_mov_b32 s55, s36
	s_cmp_lg_u32 s37, 0
	s_cselect_b32 s36, 0, -1
	s_cselect_b32 s37, -1, 0
	s_mov_b32 s0, 0x5000
	s_mov_b64 exec, s[36:37]
	s_add_i32 m0, s0, s55
	s_nop 0
	global_load_lds_dwordx4 v109, s[62:63]
	s_mov_b64 exec, -1
	s_add_i32 m0, s0, s53
	s_nop 0
	global_load_lds_dwordx4 v0, s[64:65]
	global_load_lds_dwordx4 v0, s[64:65] offset:1024
	s_add_u32 s62, s62, 0x1000
	s_addc_u32 s63, s63, 0
	s_add_u32 s64, s64, 0x4000
	s_addc_u32 s65, s65, 0
	s_mov_b32 s0, 0xa000
	s_mov_b64 exec, s[36:37]
	s_add_i32 m0, s0, s55
	s_nop 0
	global_load_lds_dwordx4 v109, s[62:63]
	s_mov_b64 exec, -1
	s_add_i32 m0, s0, s53
	s_nop 0
	global_load_lds_dwordx4 v0, s[64:65]
	global_load_lds_dwordx4 v0, s[64:65] offset:1024
	s_add_u32 s62, s62, 0x1000
	s_addc_u32 s63, s63, 0
	s_add_u32 s64, s64, 0x4000
	s_addc_u32 s65, s65, 0
	s_mov_b32 s0, 0xf000
	s_mov_b64 exec, s[36:37]
	s_add_i32 m0, s0, s55
	s_nop 0
	global_load_lds_dwordx4 v109, s[62:63]
	s_mov_b64 exec, -1
	s_add_i32 m0, s0, s53
	s_nop 0
	global_load_lds_dwordx4 v0, s[64:65]
	global_load_lds_dwordx4 v0, s[64:65] offset:1024
	s_add_u32 s62, s62, 0x1000
	s_addc_u32 s63, s63, 0
	s_add_u32 s64, s64, 0x4000
	s_addc_u32 s65, s65, 0
	s_mov_b32 s0, 0x14000
	s_mov_b64 exec, s[36:37]
	s_add_i32 m0, s0, s55
	s_nop 0
	global_load_lds_dwordx4 v109, s[62:63]
	s_mov_b64 exec, -1
	s_add_i32 m0, s0, s53
	s_nop 0
	global_load_lds_dwordx4 v0, s[64:65]
	global_load_lds_dwordx4 v0, s[64:65] offset:1024
	s_add_u32 s62, s62, 0x1000
	s_addc_u32 s63, s63, 0
	s_add_u32 s64, s64, 0x4000
	s_addc_u32 s65, s65, 0
	global_load_dwordx4 v[16:19], v0, s[58:59]
	global_load_dwordx4 v[20:23], v0, s[58:59] offset:1024
	global_load_dwordx4 v[24:27], v1, s[60:61]
	s_add_u32 s58, s58, 0x4000
	s_addc_u32 s59, s59, 0
	s_add_u32 s60, s60, 0x200
	s_addc_u32 s61, s61, 0
	global_load_dwordx4 v[28:31], v0, s[58:59]
	global_load_dwordx4 v[32:35], v0, s[58:59] offset:1024
	global_load_dwordx4 v[36:39], v1, s[60:61]
	s_add_u32 s58, s58, 0x4000
	s_addc_u32 s59, s59, 0
	s_add_u32 s60, s60, 0x200
	s_addc_u32 s61, s61, 0
	v_mov_b32_e32 v8, 0
	v_mov_b32_e32 v9, 0
	v_mov_b32_e32 v10, 0
	v_mov_b32_e32 v11, 0
	v_mov_b32_e32 v12, 0
	v_mov_b32_e32 v13, 0
	v_mov_b32_e32 v14, 0
	v_mov_b32_e32 v15, 0
	s_mov_b32 s54, 0
	s_mov_b32 s68, 0x5000
	s_waitcnt vmcnt(0)
	s_barrier
.Lgla_loop:
	s_waitcnt vmcnt(11)
	v_add_u32_e32 v5, s68, v0
	ds_read_b128 v[52:55], v5
	ds_read_b128 v[56:59], v5 offset:1024
	ds_read_b128 v[60:63], v5 offset:2048
	ds_read_b128 v[64:67], v5 offset:3072
	v_pk_mul_f32 v[8:9], v[8:9], v[24:25]
	v_pk_mul_f32 v[10:11], v[10:11], v[26:27]
	v_pk_mul_f32 v[12:13], v[12:13], v[24:25]
	v_pk_mul_f32 v[14:15], v[14:15], v[26:27]
	s_and_b32 s69, s54, 1
	s_mulk_i32 s69, 0x2200
	v_add_u32_e32 v6, s69, v3
	v_add_u32_e32 v7, s69, v4
	s_waitcnt lgkmcnt(0)
	s_nop 0
	v_mfma_f32_16x16x32_bf16 v[8:11], v[16:19], v[52:55], v[8:11]
	v_mfma_f32_16x16x32_bf16 v[12:15], v[16:19], v[60:63], v[12:15]
	v_mfma_f32_16x16x32_bf16 v[8:11], v[20:23], v[56:59], v[8:11]
	v_mfma_f32_16x16x32_bf16 v[12:15], v[20:23], v[64:67], v[12:15]
	global_load_dwordx4 v[40:43], v0, s[58:59]
	global_load_dwordx4 v[44:47], v0, s[58:59] offset:1024
	global_load_dwordx4 v[48:51], v1, s[60:61]
	s_add_u32 s58, s58, 0x4000
	s_addc_u32 s59, s59, 0
	s_add_u32 s60, s60, 0x200
	s_addc_u32 s61, s61, 0
	s_nop 7
	v_cvt_pk_bf16_f32 v104, v8, v9
	v_cvt_pk_bf16_f32 v105, v10, v11
	v_cvt_pk_bf16_f32 v106, v12, v13
	v_cvt_pk_bf16_f32 v107, v14, v15
	ds_write_b64 v6, v[104:105]
	ds_write_b64 v6, v[106:107] offset:4352
	s_waitcnt vmcnt(11)
	s_waitcnt lgkmcnt(0)
	s_barrier
	v_add_u32_e32 v5, s68, v108
	ds_read_b128 v[68:71], v7
	ds_read_b128 v[72:75], v7 offset:64
	ds_read_b128 v[76:79], v7 offset:128
	ds_read_b128 v[80:83], v7 offset:192
	ds_read_b128 v[84:87], v5
	ds_read_b128 v[88:91], v5 offset:1024
	ds_read_b128 v[92:95], v5 offset:2048
	ds_read_b128 v[96:99], v5 offset:3072
	s_add_i32 s0, s68, 0xffffb000
	s_cmp_lg_u32 s68, 0x5000
	s_cselect_b32 s0, s0, 0x19000
	s_mov_b64 exec, s[36:37]
	s_add_i32 m0, s0, s55
	s_nop 0
	global_load_lds_dwordx4 v109, s[62:63]
	s_mov_b64 exec, -1
	s_add_i32 m0, s0, s53
	s_nop 0
	global_load_lds_dwordx4 v0, s[64:65]
	global_load_lds_dwordx4 v0, s[64:65] offset:1024
	s_add_u32 s62, s62, 0x1000
	s_addc_u32 s63, s63, 0
	s_add_u32 s64, s64, 0x4000
	s_addc_u32 s65, s65, 0
	s_waitcnt lgkmcnt(0)
	v_mfma_f32_16x16x32_bf16 v[100:103], v[68:71], v[84:87], 0
	v_mfma_f32_16x16x32_bf16 v[100:103], v[72:75], v[88:91], v[100:103]
	v_mfma_f32_16x16x32_bf16 v[100:103], v[76:79], v[92:95], v[100:103]
	v_mfma_f32_16x16x32_bf16 v[100:103], v[80:83], v[96:99], v[100:103]
	s_add_i32 s68, s68, 0x5000
	s_cmp_lg_u32 s68, 0x1e000
	s_cselect_b32 s68, s68, 0x5000
	s_nop 7
	v_pk_mul_f32 v[100:101], v[100:101], s[22:23] op_sel_hi:[1,0]
	v_pk_mul_f32 v[102:103], v[102:103], s[22:23] op_sel_hi:[1,0]
	s_cmpk_lt_u32 s54, 0x20
	v_cvt_pk_bf16_f32 v104, v100, v101
	v_cvt_pk_bf16_f32 v105, v102, v103
	s_cbranch_scc0 .Lgla_nost0
	global_store_dwordx2 v2, v[104:105], s[66:67]
; __device__ __forceinline__ void gla_item(LAS unsigned char* lds, int item, const bf16_t* KDT, const float* DEC, const bf16_t* GVT, const bf16_t* GQF, bf16_t* OG) {
;     ...
;     for (int c = 0; c < 30; c += 3) {
;         GLA_LOAD(s2, c + 2); GLA_STEP(s0, c);
;         GLA_LOAD(s0, c + 3); GLA_STEP(s1, c + 1);
;         GLA_LOAD(s1, c + 4); GLA_STEP(s2, c + 2);
;     }
.Lgla_nost0:
	s_add_u32 s66, s66, 0x1000
	s_addc_u32 s67, s67, 0
	s_add_i32 s54, s54, 1
	s_waitcnt vmcnt(11)
	v_add_u32_e32 v5, s68, v0
	ds_read_b128 v[52:55], v5
	ds_read_b128 v[56:59], v5 offset:1024
	ds_read_b128 v[60:63], v5 offset:2048
	ds_read_b128 v[64:67], v5 offset:3072
	v_pk_mul_f32 v[8:9], v[8:9], v[36:37]
	v_pk_mul_f32 v[10:11], v[10:11], v[38:39]
	v_pk_mul_f32 v[12:13], v[12:13], v[36:37]
	v_pk_mul_f32 v[14:15], v[14:15], v[38:39]
	s_and_b32 s69, s54, 1
	s_mulk_i32 s69, 0x2200
	v_add_u32_e32 v6, s69, v3
	v_add_u32_e32 v7, s69, v4
	s_waitcnt lgkmcnt(0)
	s_nop 0
	v_mfma_f32_16x16x32_bf16 v[8:11], v[28:31], v[52:55], v[8:11]
	v_mfma_f32_16x16x32_bf16 v[12:15], v[28:31], v[60:63], v[12:15]
	v_mfma_f32_16x16x32_bf16 v[8:11], v[32:35], v[56:59], v[8:11]
	v_mfma_f32_16x16x32_bf16 v[12:15], v[32:35], v[64:67], v[12:15]
	global_load_dwordx4 v[16:19], v0, s[58:59]
	global_load_dwordx4 v[20:23], v0, s[58:59] offset:1024
	global_load_dwordx4 v[24:27], v1, s[60:61]
	s_add_u32 s58, s58, 0x4000
	s_addc_u32 s59, s59, 0
	s_add_u32 s60, s60, 0x200
	s_addc_u32 s61, s61, 0
	s_nop 7
	v_cvt_pk_bf16_f32 v104, v8, v9
	v_cvt_pk_bf16_f32 v105, v10, v11
	v_cvt_pk_bf16_f32 v106, v12, v13
	v_cvt_pk_bf16_f32 v107, v14, v15
	ds_write_b64 v6, v[104:105]
	ds_write_b64 v6, v[106:107] offset:4352
	s_waitcnt vmcnt(11)
	s_waitcnt lgkmcnt(0)
	s_barrier
	v_add_u32_e32 v5, s68, v108
	ds_read_b128 v[68:71], v7
	ds_read_b128 v[72:75], v7 offset:64
	ds_read_b128 v[76:79], v7 offset:128
	ds_read_b128 v[80:83], v7 offset:192
	ds_read_b128 v[84:87], v5
	ds_read_b128 v[88:91], v5 offset:1024
	ds_read_b128 v[92:95], v5 offset:2048
	ds_read_b128 v[96:99], v5 offset:3072
	s_add_i32 s0, s68, 0xffffb000
	s_cmp_lg_u32 s68, 0x5000
	s_cselect_b32 s0, s0, 0x19000
	s_mov_b64 exec, s[36:37]
	s_add_i32 m0, s0, s55
	s_nop 0
	global_load_lds_dwordx4 v109, s[62:63]
	s_mov_b64 exec, -1
	s_add_i32 m0, s0, s53
	s_nop 0
	global_load_lds_dwordx4 v0, s[64:65]
	global_load_lds_dwordx4 v0, s[64:65] offset:1024
	s_add_u32 s62, s62, 0x1000
	s_addc_u32 s63, s63, 0
	s_add_u32 s64, s64, 0x4000
	s_addc_u32 s65, s65, 0
	s_waitcnt lgkmcnt(0)
	v_mfma_f32_16x16x32_bf16 v[100:103], v[68:71], v[84:87], 0
	v_mfma_f32_16x16x32_bf16 v[100:103], v[72:75], v[88:91], v[100:103]
	v_mfma_f32_16x16x32_bf16 v[100:103], v[76:79], v[92:95], v[100:103]
	v_mfma_f32_16x16x32_bf16 v[100:103], v[80:83], v[96:99], v[100:103]
	s_add_i32 s68, s68, 0x5000
	s_cmp_lg_u32 s68, 0x1e000
	s_cselect_b32 s68, s68, 0x5000
	s_nop 7
	v_pk_mul_f32 v[100:101], v[100:101], s[22:23] op_sel_hi:[1,0]
	v_pk_mul_f32 v[102:103], v[102:103], s[22:23] op_sel_hi:[1,0]
	s_cmpk_lt_u32 s54, 0x20
	v_cvt_pk_bf16_f32 v104, v100, v101
	v_cvt_pk_bf16_f32 v105, v102, v103
	s_cbranch_scc0 .Lgla_nost1
	global_store_dwordx2 v2, v[104:105], s[66:67]
.Lgla_nost1:
	s_add_u32 s66, s66, 0x1000
	s_addc_u32 s67, s67, 0
	s_add_i32 s54, s54, 1
	s_waitcnt vmcnt(11)
	v_add_u32_e32 v5, s68, v0
	ds_read_b128 v[52:55], v5
	ds_read_b128 v[56:59], v5 offset:1024
	ds_read_b128 v[60:63], v5 offset:2048
	ds_read_b128 v[64:67], v5 offset:3072
	v_pk_mul_f32 v[8:9], v[8:9], v[48:49]
	v_pk_mul_f32 v[10:11], v[10:11], v[50:51]
	v_pk_mul_f32 v[12:13], v[12:13], v[48:49]
	v_pk_mul_f32 v[14:15], v[14:15], v[50:51]
	s_and_b32 s69, s54, 1
	s_mulk_i32 s69, 0x2200
	v_add_u32_e32 v6, s69, v3
	v_add_u32_e32 v7, s69, v4
	s_waitcnt lgkmcnt(0)
	s_nop 0
	v_mfma_f32_16x16x32_bf16 v[8:11], v[40:43], v[52:55], v[8:11]
	v_mfma_f32_16x16x32_bf16 v[12:15], v[40:43], v[60:63], v[12:15]
	v_mfma_f32_16x16x32_bf16 v[8:11], v[44:47], v[56:59], v[8:11]
	v_mfma_f32_16x16x32_bf16 v[12:15], v[44:47], v[64:67], v[12:15]
	global_load_dwordx4 v[28:31], v0, s[58:59]
	global_load_dwordx4 v[32:35], v0, s[58:59] offset:1024
	global_load_dwordx4 v[36:39], v1, s[60:61]
	s_add_u32 s58, s58, 0x4000
	s_addc_u32 s59, s59, 0
	s_add_u32 s60, s60, 0x200
	s_addc_u32 s61, s61, 0
	s_nop 7
	v_cvt_pk_bf16_f32 v104, v8, v9
	v_cvt_pk_bf16_f32 v105, v10, v11
	v_cvt_pk_bf16_f32 v106, v12, v13
	v_cvt_pk_bf16_f32 v107, v14, v15
	ds_write_b64 v6, v[104:105]
	ds_write_b64 v6, v[106:107] offset:4352
	s_waitcnt vmcnt(11)
	s_waitcnt lgkmcnt(0)
	s_barrier
	v_add_u32_e32 v5, s68, v108
	ds_read_b128 v[68:71], v7
	ds_read_b128 v[72:75], v7 offset:64
	ds_read_b128 v[76:79], v7 offset:128
	ds_read_b128 v[80:83], v7 offset:192
	ds_read_b128 v[84:87], v5
	ds_read_b128 v[88:91], v5 offset:1024
	ds_read_b128 v[92:95], v5 offset:2048
	ds_read_b128 v[96:99], v5 offset:3072
	s_add_i32 s0, s68, 0xffffb000
	s_cmp_lg_u32 s68, 0x5000
	s_cselect_b32 s0, s0, 0x19000
	s_mov_b64 exec, s[36:37]
	s_add_i32 m0, s0, s55
	s_nop 0
	global_load_lds_dwordx4 v109, s[62:63]
	s_mov_b64 exec, -1
	s_add_i32 m0, s0, s53
	s_nop 0
	global_load_lds_dwordx4 v0, s[64:65]
	global_load_lds_dwordx4 v0, s[64:65] offset:1024
	s_add_u32 s62, s62, 0x1000
	s_addc_u32 s63, s63, 0
	s_add_u32 s64, s64, 0x4000
	s_addc_u32 s65, s65, 0
	s_waitcnt lgkmcnt(0)
	v_mfma_f32_16x16x32_bf16 v[100:103], v[68:71], v[84:87], 0
	v_mfma_f32_16x16x32_bf16 v[100:103], v[72:75], v[88:91], v[100:103]
	v_mfma_f32_16x16x32_bf16 v[100:103], v[76:79], v[92:95], v[100:103]
	v_mfma_f32_16x16x32_bf16 v[100:103], v[80:83], v[96:99], v[100:103]
	s_add_i32 s68, s68, 0x5000
	s_cmp_lg_u32 s68, 0x1e000
	s_cselect_b32 s68, s68, 0x5000
	s_nop 7
	v_pk_mul_f32 v[100:101], v[100:101], s[22:23] op_sel_hi:[1,0]
	v_pk_mul_f32 v[102:103], v[102:103], s[22:23] op_sel_hi:[1,0]
	s_cmpk_lt_u32 s54, 0x20
	v_cvt_pk_bf16_f32 v104, v100, v101
	v_cvt_pk_bf16_f32 v105, v102, v103
	s_cbranch_scc0 .Lgla_nost2
	global_store_dwordx2 v2, v[104:105], s[66:67]
